# diff2 staging: tile-ahead constants folded into the per-lane K/V bases (1 and 3 address instructions per tile instead of 5 and 9)
# baseline (speedup 1.0000x reference)
; #define LAS __attribute__((address_space(3)))
; #define D2_LOADK(tt) do { const unsigned char* zt_ = Zt + (size_t)(tt) * (64 * 1024 * 2); gk0 = *(const v4u*)(zt_ + oK); gk1 = *(const v4u*)(zt_ + oK + 1024); } while (0)
; #define D2_LOADV(tt) do { const unsigned char* zt_ = ZtV + (size_t)(tt) * (64 * 1024 * 2); gv0 = *(const v4u*)(zt_ + oV); gv1 = *(const v4u*)(zt_ + oV + 32 * 1024 * 2); } while (0)
; __device__ __forceinline__ void diff2_item(const Params& p, LAS unsigned char* lds, const int item, const float lam, const float lam_init) {
;     ...
;     v16f O[4]; float m_ = NEGBIG, l_ = 0.f;
; #pragma unroll
;     for (int eb = 0; eb < 4; ++eb)
; #pragma unroll
;         for (int i = 0; i < 16; ++i) O[eb][i] = 0.f;
;     const int rowK = tid >> 3, cc = tid & 7, rowV = tid >> 4, ccV = tid & 15;
;     const unsigned char* Zt = (const unsigned char*)(Z + (size_t)T * OFF_DK + ((size_t)b * 2048) * 1024 + hh * 64);
;     const unsigned char* ZtV = (const unsigned char*)(Z + (size_t)T * OFF_DV + ((size_t)b * 2048) * 1024 + hh * 128);
;     const unsigned oK = (unsigned)(rowK * 1024 + cc * 8) * 2u;
;     const unsigned oV = (unsigned)(rowV * 1024 + ccV * 8) * 2u;
;     LAS unsigned char* dK = lds + rowK * 144 + cc * 16;
;     LAS unsigned char* dV = lds + D2_VR + rowV * 320 + ccV * 16;
;     ...
;     v4u gk0, gk1, gv0, gv1;
;     D2_LOADK(0);
;     *(LAS v4u*)dK = gk0; *(LAS v4u*)(dK + D2_K1) = gk1;
;     D2_LOADK(1); D2_LOADV(0);
;     __syncthreads();
;     const float c1 = 0.125f * LOG2E;
;     const LAS unsigned char* kb0 = lds + mp * D2_K1 + r * 144 + h * 16;
;     const int q_ = (lane >> 2) & 3, p_ = lane & 3, g1_ = (lane >> 4) & 1;
;     const LAS unsigned char* vb_lane = lds + D2_VR + ((4 * h + q_) * 320 + (16 * g1_ + 4 * p_) * 2);
.LBB0_325:
	s_or_b64 exec, exec, s[10:11]
	s_movk_i32 s10, 0x140
	v_mul_lo_u32 v6, v7, s10
	v_readlane_b32 s10, v248, 33
	s_add_u32 s10, s10, s6
	v_readlane_b32 s11, v248, 34
	s_addc_u32 s11, s11, s7
	v_and_b32_e32 v177, 63, v2
	v_lshlrev_b32_e32 v176, 3, v8
	v_add3_u32 v182, 0, v6, v148
	v_lshrrev_b32_e32 v6, 2, v2
	v_lshlrev_b32_e32 v7, 2, v8
	v_and_b32_e32 v8, 16, v2
	v_lshlrev_b32_e32 v2, 2, v2
	v_lshl_add_u64 v[150:151], s[10:11], 0, v[0:1]
	s_mov_b64 s[98:99], 0x1aa40000
	v_lshl_add_u64 v[150:151], v[150:151], 0, s[98:99]
	v_readlane_b32 s10, v248, 35
	v_and_or_b32 v6, v6, 3, v7
	v_and_or_b32 v2, v2, 12, v8
	s_add_u32 s6, s10, s6
	v_readlane_b32 s10, v248, 36
	v_mul_u32_u24_e32 v6, 0x140, v6
	v_lshlrev_b32_e32 v2, 1, v2
	v_add3_u32 v0, s52, v3, v174
	s_addc_u32 s7, s10, s7
	v_mov_b32_e32 v14, v1
	v_mov_b32_e32 v15, v1
	v_add3_u32 v180, 0, v6, v2
	v_sub_u32_e32 v183, v7, v0
	v_lshl_add_u64 v[152:153], s[6:7], 0, v[4:5]
	s_mov_b64 s[98:99], 0x1ca20000
	v_lshl_add_u64 v[152:153], v[152:153], 0, s[98:99]
	v_mov_b32_e32 v0, v1
	v_mov_b32_e32 v2, v1
	v_mov_b32_e32 v3, v1
	v_mov_b32_e32 v4, v1
	v_mov_b32_e32 v5, v1
	v_mov_b32_e32 v6, v1
	v_mov_b32_e32 v7, v1
	v_mov_b32_e32 v8, v1
	v_mov_b32_e32 v9, v1
	v_mov_b32_e32 v10, v1
	v_mov_b32_e32 v11, v1
	v_mov_b32_e32 v12, v1
	v_mov_b32_e32 v13, v1
	v_mov_b64_e32 v[64:65], v[14:15]
	v_mov_b64_e32 v[48:49], v[14:15]
	v_mov_b64_e32 v[32:33], v[14:15]
	v_mov_b64_e32 v[62:63], v[12:13]
	v_mov_b64_e32 v[60:61], v[10:11]
	v_mov_b64_e32 v[58:59], v[8:9]
	v_mov_b64_e32 v[56:57], v[6:7]
	v_mov_b64_e32 v[54:55], v[4:5]
	v_mov_b64_e32 v[52:53], v[2:3]
	v_mov_b64_e32 v[50:51], v[0:1]
	v_mov_b64_e32 v[46:47], v[12:13]
	v_mov_b64_e32 v[44:45], v[10:11]
	v_mov_b64_e32 v[42:43], v[8:9]
	v_mov_b64_e32 v[40:41], v[6:7]
	v_mov_b64_e32 v[38:39], v[4:5]
	v_mov_b64_e32 v[36:37], v[2:3]
	v_mov_b64_e32 v[34:35], v[0:1]
	v_mov_b64_e32 v[30:31], v[12:13]
	v_mov_b64_e32 v[28:29], v[10:11]
	v_mov_b64_e32 v[26:27], v[8:9]
	v_mov_b64_e32 v[24:25], v[6:7]
	v_mov_b64_e32 v[22:23], v[4:5]
	v_mov_b64_e32 v[20:21], v[2:3]
	v_mov_b64_e32 v[18:19], v[0:1]
	v_mov_b64_e32 v[16:17], v[14:15]
	s_mov_b32 s19, 0
	v_mov_b32_e32 v184, 0xf149f2ca
	v_mov_b32_e32 v154, 0
	s_mov_b64 s[6:7], 0
	v_mov_b64_e32 v[14:15], v[12:13]
	v_mov_b64_e32 v[12:13], v[10:11]
	v_mov_b64_e32 v[10:11], v[8:9]
	v_mov_b64_e32 v[8:9], v[6:7]
	v_mov_b64_e32 v[6:7], v[4:5]
	v_mov_b64_e32 v[4:5], v[2:3]
	v_mov_b64_e32 v[2:3], v[0:1]
	s_barrier

; #define D2_LOADK(tt) do { const unsigned char* zt_ = Zt + (size_t)(tt) * (64 * 1024 * 2); gk0 = *(const v4u*)(zt_ + oK); gk1 = *(const v4u*)(zt_ + oK + 1024); } while (0)
; #define D2_LOADV(tt) do { const unsigned char* zt_ = ZtV + (size_t)(tt) * (64 * 1024 * 2); gv0 = *(const v4u*)(zt_ + oV); gv1 = *(const v4u*)(zt_ + oV + 32 * 1024 * 2); } while (0)
; __device__ __forceinline__ void diff2_item(const Params& p, LAS unsigned char* lds, const int item, const float lam, const float lam_init) {
;     ...
;         if (t + 2 < 32) D2_LOADK(t + 2);
;         if (t + 1 < 32) D2_LOADV(t + 1);
.LBB0_331:
	v_lshl_add_u64 v[118:119], v[150:151], 0, s[6:7]
	global_load_dwordx4 v[114:117], v[118:119], off
	s_nop 0
	global_load_dwordx4 v[118:121], v[118:119], off offset:1024
	v_cndmask_b32_e64 v0, 0, 1, s[10:11]
	v_cmp_ne_u32_e64 s[40:41], 1, v0
	s_andn2_b64 vcc, exec, s[10:11]
	s_cbranch_vccnz .LBB0_330
.LBB0_332:
	v_lshl_add_u64 v[124:125], v[152:153], 0, s[6:7]
	s_mov_b64 s[98:99], 0x10000
	v_lshl_add_u64 v[126:127], v[124:125], 0, s[98:99]
	global_load_dwordx4 v[122:125], v[124:125], off
	s_nop 0
	global_load_dwordx4 v[126:129], v[126:127], off
	s_and_saveexec_b64 s[10:11], s[38:39]
	s_xor_b64 s[10:11], exec, s[10:11]
	s_cbranch_execz .LBB0_335
